# stack of exact micro-edits on the ballot-trim version: row-scale reload with all 8 loads in flight + softmax exp results written straight to their home registers (24 v_mov removed)
# baseline (speedup 1.0000x reference)
; __device__ __forceinline__ void attn_unit(KArg P, int L, int b, int nb, int kvh, LAS unsigned char* lds) {
;     ...
;         mx = fmaxf(mx, __shfl_xor(mx, 16)); mx = fmaxf(mx, __shfl_xor(mx, 32));
;         float sum = 0.f;
; #pragma unroll
;         for (int tt = 0; tt < 10; ++tt)
; #pragma unroll
;             for (int r = 0; r < 4; ++r) { const float p = (sc[tt][r] > -1e29f) ? __expf(sc[tt][r] - mx) : 0.f; sc[tt][r] = p; sum += p; }
;         sum += __shfl_xor(sum, 16); sum += __shfl_xor(sum, 32);
;         const float inv = 1.0f / (sum + __expf(sink - mx));
.LBB0_583:
	ds_bpermute_b32 v146, v180, v187
	v_max_f32_e32 v147, v187, v187
	s_waitcnt lgkmcnt(0)
	v_max_f32_e32 v146, v146, v146
	v_max_f32_e32 v146, v147, v146
	ds_bpermute_b32 v147, v181, v146
	s_waitcnt lgkmcnt(0)
	v_max_f32_e32 v147, v147, v147
	v_max_f32_e32 v187, v146, v147
	v_sub_f32_e32 v146, v221, v187
	v_mul_f32_e32 v146, 0x3fb8aa3b, v146
	v_sub_f32_e32 v147, v220, v187
	v_exp_f32_e32 v146, v146
	v_mul_f32_e32 v147, 0x3fb8aa3b, v147
	v_exp_f32_e32 v147, v147
	v_sub_f32_e32 v163, v189, v187
	s_nop 0
	v_add_f32_e32 v148, 0, v146
	v_mul_f32_e32 v163, 0x3fb8aa3b, v163
	s_nop 0
	v_add_f32_e32 v150, v147, v148
	v_sub_f32_e32 v148, v219, v187
	v_mul_f32_e32 v148, 0x3fb8aa3b, v148
	v_exp_f32_e32 v148, v148
	v_exp_f32_e32 v189, v163
	v_sub_f32_e32 v164, v199, v187
	s_nop 0
	v_add_f32_e32 v153, v148, v150
	v_sub_f32_e32 v150, v218, v187
	v_mul_f32_e32 v150, 0x3fb8aa3b, v150
	v_exp_f32_e32 v150, v150
	v_mul_f32_e32 v164, 0x3fb8aa3b, v164
	v_sub_f32_e32 v165, v198, v187
	s_nop 0
	v_add_f32_e32 v162, v150, v153
	v_sub_f32_e32 v153, v217, v187
	v_mul_f32_e32 v153, 0x3fb8aa3b, v153
	v_exp_f32_e32 v153, v153
	v_exp_f32_e32 v164, v164
	v_mul_f32_e32 v165, 0x3fb8aa3b, v165
	s_nop 0
	v_add_f32_e32 v162, v153, v162
	v_sub_f32_e32 v168, v194, v187
	v_sub_f32_e32 v163, v192, v187
	v_mul_f32_e32 v163, 0x3fb8aa3b, v163
	v_exp_f32_e32 v192, v163
	v_add_f32_e32 v162, v189, v162
	v_exp_f32_e32 v165, v165
	v_sub_f32_e32 v163, v196, v187
	v_mul_f32_e32 v163, 0x3fb8aa3b, v163
	v_exp_f32_e32 v196, v163
	v_add_f32_e32 v162, v192, v162
	v_mul_f32_e32 v168, 0x3fb8aa3b, v168
	v_sub_f32_e32 v163, v191, v187
	v_mul_f32_e32 v163, 0x3fb8aa3b, v163
	v_exp_f32_e32 v191, v163
	v_add_f32_e32 v162, v196, v162
	v_sub_f32_e32 v169, v193, v187
	v_sub_f32_e32 v163, v195, v187
	v_mul_f32_e32 v163, 0x3fb8aa3b, v163
	v_exp_f32_e32 v195, v163
	v_add_f32_e32 v162, v191, v162
	v_exp_f32_e32 v168, v168
	v_sub_f32_e32 v163, v197, v187
	v_mul_f32_e32 v163, 0x3fb8aa3b, v163
	v_exp_f32_e32 v197, v163
	v_add_f32_e32 v162, v195, v162
	v_mul_f32_e32 v169, 0x3fb8aa3b, v169
	v_sub_f32_e32 v163, v201, v187
	v_mul_f32_e32 v163, 0x3fb8aa3b, v163
	v_exp_f32_e32 v201, v163
	v_add_f32_e32 v162, v197, v162
	v_sub_f32_e32 v170, v190, v187
	v_sub_f32_e32 v163, v202, v187
	v_mul_f32_e32 v163, 0x3fb8aa3b, v163
	v_exp_f32_e32 v202, v163
	v_add_f32_e32 v162, v201, v162
	v_exp_f32_e32 v169, v169
	v_sub_f32_e32 v163, v204, v187
	v_mul_f32_e32 v163, 0x3fb8aa3b, v163
	v_exp_f32_e32 v204, v163
	v_add_f32_e32 v162, v202, v162
	v_mul_f32_e32 v170, 0x3fb8aa3b, v170
	v_sub_f32_e32 v163, v207, v187
	v_mul_f32_e32 v163, 0x3fb8aa3b, v163
	v_exp_f32_e32 v207, v163
	v_add_f32_e32 v162, v204, v162
	v_sub_f32_e32 v171, v188, v187
	v_sub_f32_e32 v163, v211, v187
	v_mul_f32_e32 v163, 0x3fb8aa3b, v163
	v_exp_f32_e32 v211, v163
	v_add_f32_e32 v162, v207, v162
	v_exp_f32_e32 v170, v170
	v_sub_f32_e32 v163, v205, v187
	v_mul_f32_e32 v163, 0x3fb8aa3b, v163
	v_exp_f32_e32 v205, v163
	v_add_f32_e32 v162, v211, v162
	v_mul_f32_e32 v171, 0x3fb8aa3b, v171
	v_sub_f32_e32 v163, v210, v187
	v_mul_f32_e32 v163, 0x3fb8aa3b, v163
	v_exp_f32_e32 v210, v163
	v_add_f32_e32 v162, v205, v162
	v_sub_f32_e32 v172, v186, v187
	v_sub_f32_e32 v163, v213, v187
	v_mul_f32_e32 v163, 0x3fb8aa3b, v163
	v_exp_f32_e32 v213, v163
	v_add_f32_e32 v162, v210, v162
	v_exp_f32_e32 v171, v171
	v_sub_f32_e32 v163, v215, v187
	v_mul_f32_e32 v163, 0x3fb8aa3b, v163
	v_exp_f32_e32 v215, v163
	v_add_f32_e32 v162, v213, v162
	v_mul_f32_e32 v172, 0x3fb8aa3b, v172
	v_sub_f32_e32 v163, v216, v187
	v_mul_f32_e32 v163, 0x3fb8aa3b, v163
	v_exp_f32_e32 v216, v163
	v_sub_f32_e32 v173, v185, v187
	v_add_f32_e32 v162, v215, v162
	v_sub_f32_e32 v163, v214, v187
	v_mul_f32_e32 v163, 0x3fb8aa3b, v163
	v_exp_f32_e32 v214, v163
	v_exp_f32_e32 v172, v172
	v_mul_f32_e32 v173, 0x3fb8aa3b, v173
	v_sub_f32_e32 v163, v212, v187
	v_mul_f32_e32 v163, 0x3fb8aa3b, v163
	v_exp_f32_e32 v212, v163
	v_sub_f32_e32 v174, v184, v187
	v_add_f32_e32 v162, v216, v162
	v_sub_f32_e32 v163, v209, v187
	v_mul_f32_e32 v163, 0x3fb8aa3b, v163
	v_exp_f32_e32 v209, v163
	v_exp_f32_e32 v173, v173
	v_mul_f32_e32 v174, 0x3fb8aa3b, v174
	v_sub_f32_e32 v163, v208, v187
	v_mul_f32_e32 v163, 0x3fb8aa3b, v163
	v_exp_f32_e32 v208, v163
	v_add_f32_e32 v162, v214, v162
	v_exp_f32_e32 v174, v174
	v_sub_f32_e32 v163, v206, v187
	v_mul_f32_e32 v163, 0x3fb8aa3b, v163
	v_exp_f32_e32 v206, v163
	v_add_f32_e32 v162, v212, v162
	v_add_f32_e32 v162, v209, v162
	v_sub_f32_e32 v163, v203, v187
	v_mul_f32_e32 v163, 0x3fb8aa3b, v163
	v_exp_f32_e32 v203, v163
	v_add_f32_e32 v162, v208, v162
	v_add_f32_e32 v162, v206, v162
	v_sub_f32_e32 v163, v200, v187
	v_mul_f32_e32 v163, 0x3fb8aa3b, v163
	v_exp_f32_e32 v163, v163
	v_add_f32_e32 v162, v203, v162
	v_cvt_pk_bf16_f32 v146, v146, v147
	s_nop 0
	v_add_f32_e32 v162, v163, v162
	v_cvt_pk_bf16_f32 v147, v148, v150
	s_nop 0
	v_add_f32_e32 v162, v164, v162
	v_cvt_pk_bf16_f32 v148, v153, v189
	s_nop 0
	v_add_f32_e32 v162, v165, v162
	v_cvt_pk_bf16_f32 v189, v197, v201
	s_nop 0
	v_add_f32_e32 v162, v168, v162
	s_nop 0
	s_nop 0
	v_add_f32_e32 v162, v169, v162
	v_cvt_pk_bf16_f32 v190, v202, v204
	s_nop 0
	v_add_f32_e32 v162, v170, v162
	v_cvt_pk_bf16_f32 v188, v191, v195
	s_nop 0
	v_add_f32_e32 v162, v171, v162
	v_cvt_pk_bf16_f32 v191, v207, v211
	s_nop 0
	v_add_f32_e32 v162, v172, v162
	s_nop 0
	s_nop 0
	v_add_f32_e32 v162, v173, v162
	s_nop 0
	s_nop 0
	v_sub_f32_e32 v152, v152, v187
	v_mul_f32_e32 v152, 0x3fb8aa3b, v152
	v_exp_f32_e32 v175, v152
	v_add_f32_e32 v162, v174, v162
	v_sub_f32_e32 v151, v151, v187
	v_mul_f32_e32 v151, 0x3fb8aa3b, v151
	v_exp_f32_e32 v151, v151
	v_add_f32_e32 v152, v175, v162
	v_mov_b32_e32 v162, v151
	v_sub_f32_e32 v149, v149, v187
	v_mul_f32_e32 v149, 0x3fb8aa3b, v149
	v_exp_f32_e32 v198, v149
	v_add_f32_e32 v151, v162, v152
	v_add_f32_e32 v149, v198, v151
	ds_bpermute_b32 v151, v180, v149
	s_waitcnt lgkmcnt(0)
; #define LAS __attribute__((address_space(3)))
; __device__ __forceinline__ unsigned cvt_pk_bf16(float lo, float hi) { f32x2_t v = {lo, hi}; bf16x2_t b = __builtin_convertvector(v, bf16x2_t); return __builtin_bit_cast(unsigned, b); }
; #define MFMA16(a, b, c) __builtin_amdgcn_mfma_f32_16x16x32_bf16((a), (b), (c), 0, 0, 0)
; __device__ __forceinline__ void attn_unit(KArg P, int L, int b, int nb, int kvh, LAS unsigned char* lds) {
;     ...
;         sum += __shfl_xor(sum, 16); sum += __shfl_xor(sum, 32);
;         const float inv = 1.0f / (sum + __expf(sink - mx));
;         f32x4 oacc[4];
; #pragma unroll
;         for (int dt = 0; dt < 4; ++dt) oacc[dt] = (f32x4){0.f, 0.f, 0.f, 0.f};
; #pragma unroll
;         for (int u = 0; u < 5; ++u) {
;             v4u pb = (v4u){cvt_pk_bf16(sc[2 * u][0], sc[2 * u][1]), cvt_pk_bf16(sc[2 * u][2], sc[2 * u][3]), cvt_pk_bf16(sc[2 * u + 1][0], sc[2 * u + 1][1]), cvt_pk_bf16(sc[2 * u + 1][2], sc[2 * u + 1][3])};
;             const bf16x8 pfr = __builtin_bit_cast(bf16x8, pb);
; #pragma unroll
;             for (int dt = 0; dt < 4; ++dt) {
;                 const int sw = (dt * 2 + (c >> 3)) & 7;
;                 const LAS unsigned char* vr = lds + AT_VT + (dt * 16 + c) * 528;
;                 const v2u lo = *(const LAS v2u*)(vr + ((((tile0 + 2 * u) * 4 + g) ^ sw) * 8)), hi = *(const LAS v2u*)(vr + ((((tile0 + 2 * u + 1) * 4 + g) ^ sw) * 8));
;                 const v4u av = (v4u){lo.x, lo.y, hi.x, hi.y};
;                 oacc[dt] = MFMA16(__builtin_bit_cast(bf16x8, av), pfr, oacc[dt]); } }
; #pragma unroll
;         for (int dt = 0; dt < 4; ++dt) { const f32x4 o = oacc[dt] * inv; v2u wv; wv.x = cvt_pk_bf16(o[0], o[1]); wv.y = cvt_pk_bf16(o[2], o[3]);
;             *(v2u*)(qrow + dt * 16 + 4 * g) = wv; }
	v_add_f32_e32 v149, v149, v151
	ds_bpermute_b32 v151, v181, v149
	s_waitcnt lgkmcnt(0)
	v_add_f32_e32 v149, v149, v151
	s_waitcnt vmcnt(0)
	v_sub_f32_e32 v151, v183, v187
	v_mul_f32_e32 v151, 0x3fb8aa3b, v151
	v_exp_f32_e32 v151, v151
	s_nop 0
	v_add_f32_e32 v183, v151, v149
	v_cvt_pk_bf16_f32 v149, v192, v196
	s_nop 1
	v_mfma_f32_16x16x32_bf16 v[150:153], v[66:69], v[146:149], 0
	v_mfma_f32_16x16x32_bf16 v[184:187], v[70:73], v[146:149], 0
	v_mfma_f32_16x16x32_bf16 v[218:221], v[74:77], v[146:149], 0
	v_mfma_f32_16x16x32_bf16 v[146:149], v[78:81], v[146:149], 0
	v_mfma_f32_16x16x32_bf16 v[150:153], v[82:85], v[188:191], v[150:153]
	v_mfma_f32_16x16x32_bf16 v[184:187], v[86:89], v[188:191], v[184:187]
	v_mfma_f32_16x16x32_bf16 v[192:195], v[90:93], v[188:191], v[218:221]
	v_mfma_f32_16x16x32_bf16 v[146:149], v[94:97], v[188:191], v[146:149]
	v_cvt_pk_bf16_f32 v188, v205, v210
	v_cvt_pk_bf16_f32 v189, v213, v215
	v_cvt_pk_bf16_f32 v190, v216, v214
	v_cvt_pk_bf16_f32 v191, v212, v209
	s_nop 1
	v_mfma_f32_16x16x32_bf16 v[150:153], v[98:101], v[188:191], v[150:153]
	v_mfma_f32_16x16x32_bf16 v[184:187], v[102:105], v[188:191], v[184:187]
	v_mfma_f32_16x16x32_bf16 v[192:195], v[106:109], v[188:191], v[192:195]
	v_mfma_f32_16x16x32_bf16 v[146:149], v[110:113], v[188:191], v[146:149]
	v_cvt_pk_bf16_f32 v188, v208, v206
	v_cvt_pk_bf16_f32 v189, v203, v163
	v_cvt_pk_bf16_f32 v190, v164, v165
	v_cvt_pk_bf16_f32 v191, v168, v169
	s_nop 1
	v_mfma_f32_16x16x32_bf16 v[150:153], v[114:117], v[188:191], v[150:153]
	v_mfma_f32_16x16x32_bf16 v[184:187], v[118:121], v[188:191], v[184:187]
	v_mfma_f32_16x16x32_bf16 v[192:195], v[122:125], v[188:191], v[192:195]
	v_mfma_f32_16x16x32_bf16 v[146:149], v[126:129], v[188:191], v[146:149]
	v_cvt_pk_bf16_f32 v191, v162, v198
	v_div_scale_f32 v162, s[96:97], v183, v183, 1.0
	v_rcp_f32_e32 v163, v162
	v_cvt_pk_bf16_f32 v188, v170, v171
	v_cvt_pk_bf16_f32 v189, v172, v173
	v_cvt_pk_bf16_f32 v190, v174, v175
	v_fma_f32 v164, -v162, v163, 1.0
	v_fmac_f32_e32 v163, v164, v163
	v_div_scale_f32 v164, vcc, 1.0, v183, 1.0
	v_mul_f32_e32 v165, v164, v163
	v_fma_f32 v168, -v162, v165, v164
	v_mfma_f32_16x16x32_bf16 v[150:153], v[130:133], v[188:191], v[150:153]
	v_fmac_f32_e32 v165, v168, v163
	v_fma_f32 v162, -v162, v165, v164
	v_div_fmas_f32 v162, v162, v163, v165
	v_mfma_f32_16x16x32_bf16 v[184:187], v[134:137], v[188:191], v[184:187]
	v_div_fixup_f32 v162, v162, v183, 1.0
	s_nop 2
	v_pk_mul_f32 v[152:153], v[152:153], v[162:163] op_sel_hi:[1,0]
	v_pk_mul_f32 v[150:151], v[150:151], v[162:163] op_sel_hi:[1,0]
	v_mfma_f32_16x16x32_bf16 v[192:195], v[138:141], v[188:191], v[192:195]
	v_lshl_add_u64 v[170:171], v[158:159], 0, s[10:11]
	v_cvt_pk_bf16_f32 v150, v150, v151
	v_cvt_pk_bf16_f32 v151, v152, v153
	v_mfma_f32_16x16x32_bf16 v[146:149], v[142:145], v[188:191], v[146:149]
	s_add_u32 s10, s10, 0x80
	global_store_dwordx2 v[170:171], v[150:151], off offset:-64
	v_pk_mul_f32 v[150:151], v[186:187], v[162:163] op_sel_hi:[1,0]
	v_pk_mul_f32 v[152:153], v[184:185], v[162:163] op_sel_hi:[1,0]
	s_addc_u32 s11, s11, 0
	v_cvt_pk_bf16_f32 v152, v152, v153
	v_cvt_pk_bf16_f32 v153, v150, v151
	s_add_u32 s8, s8, 4
	global_store_dwordx2 v[170:171], v[152:153], off offset:-32
	v_pk_mul_f32 v[150:151], v[194:195], v[162:163] op_sel_hi:[1,0]
	v_pk_mul_f32 v[152:153], v[192:193], v[162:163] op_sel_hi:[1,0]
	v_pk_mul_f32 v[148:149], v[148:149], v[162:163] op_sel_hi:[1,0]
	v_pk_mul_f32 v[146:147], v[146:147], v[162:163] op_sel_hi:[1,0]
	s_addc_u32 s9, s9, 0
	v_cvt_pk_bf16_f32 v152, v152, v153
	v_cvt_pk_bf16_f32 v153, v150, v151
	v_cvt_pk_bf16_f32 v146, v146, v147
	v_cvt_pk_bf16_f32 v147, v148, v149
	s_cmpk_lg_i32 s10, 0x200
	global_store_dwordx2 v[170:171], v[152:153], off
	global_store_dwordx2 v[170:171], v[146:147], off offset:32
	s_cbranch_scc0 .LBB0_572
